# first K-iteration with C=0 MFMAs replaces accumulator zeroing in the FFN-in (SwiGLU) GEMM body only; first seam uses the XCD barrier
# speedup vs baseline: 1.0174x; 1.0090x over previous
; __device__ __forceinline__ unsigned xb_xcc_id() { return (unsigned)__builtin_amdgcn_s_getreg((3 << 11) | 20) & 0xFu; }
; __device__ __forceinline__ void xcd_barrier(const XcdBarrier& b) {
;     asm volatile("s_waitcnt vmcnt(0)" ::: "memory");
;     __syncthreads();
;     if (threadIdx.x == 0) {
;         unsigned* bar = b.bar;
;         __builtin_amdgcn_s_waitcnt(0);
;         unsigned nloc = b.st[0], nx = b.st[1];
;         if (nloc == 0u) { xcd_barrier_complete(bar, b.x, nloc, nx); b.st[0] = nloc; b.st[1] = nx; }
; __global__ void __launch_bounds__(NTHR, 2) fwd_kernel(P p) {
;     ...
;     for (int it = 2 * p.ph_lo; it < 2 * p.ph_hi; ++it) {
;         const int ph = it >> 1;
;         if (ph == 18) continue;
;         if ((it & 1) && ph != 4 && !((DBL_MASK >> ph) & 1u)) continue;
;         if (it > 2 * p.ph_lo) {
;             if (it == 2 * p.ph_lo + 2) grid.sync();
;             else { XcdBarrier xb; xb.bar = (unsigned*)(p.ws + WS_BAR); xb.x = xb_xcc_id(); xb.st = bar_st; xcd_barrier(xb); }
;         }
.LBB0_9:
	s_ashr_i32 s3, s1, 1
	s_cmp_eq_u32 s3, 18
	s_mov_b32 s6, s1
	s_cbranch_scc1 .LBB0_8
	s_bitcmp1_b32 s6, 0
	s_cselect_b64 s[4:5], -1, 0
	s_cmp_lg_u32 s3, 4
	s_cselect_b64 s[0:1], -1, 0
	v_writelane_b32 v253, s4, 44
	s_nop 1
	v_writelane_b32 v253, s5, 45
	s_and_b64 s[4:5], s[4:5], s[0:1]
	s_and_b64 vcc, exec, s[4:5]
	s_cbranch_vccnz .LBB0_8
	v_writelane_b32 v253, s6, 46
	s_cmp_le_i32 s6, s85
	s_cbranch_scc1 .LBB0_79
	v_readlane_b32 s4, v253, 46
	v_readlane_b32 s5, v249, 14
	s_cmp_lg_u32 s4, s5
	s_mov_b64 s[4:5], -1
	s_getreg_b32 s6, hwreg(HW_REG_XCC_ID, 0, 4)
	s_waitcnt vmcnt(0)
	s_barrier
	s_mov_b64 s[4:5], exec
	v_readlane_b32 s8, v249, 12
	v_readlane_b32 s9, v249, 13
	s_and_b64 s[8:9], s[4:5], s[8:9]
	s_mov_b64 exec, s[8:9]
	s_cbranch_execz .LBB0_65
	v_readlane_b32 s7, v253, 19
	s_waitcnt vmcnt(0) expcnt(0) lgkmcnt(0)
	s_and_b32 s12, s6, 15
	v_mov_b32_e32 v0, s7
	ds_read_b32 v3, v0
	v_readlane_b32 s7, v253, 20
	s_waitcnt lgkmcnt(0)
	v_cmp_ne_u32_e32 vcc, 0, v3
	v_mov_b32_e32 v0, s7
	ds_read_b32 v2, v0
	s_cbranch_vccnz .LBB0_29
	s_mov_b32 s13, 1
	s_branch .LBB0_17

; #define PG8_STAGE(bufoff, gbase, voff) do { _Pragma("unroll") for (int _i = 0; _i < 2; ++_i) \
;         __builtin_amdgcn_global_load_lds((const unsigned*)((const char*)(gbase) + (voff)[_i]), (LAS unsigned*)(lds + (bufoff) + ldsw + _i * 8192), 16, 0, 0); } while (0)
; #define PG8_LDA(dst, b, h) do { _Pragma("unroll") for (int m = 0; m < 4; ++m) _Pragma("unroll") for (int k = 0; k < 2; ++k) dst[m][k] = *(const LAS bf16x8*)(lds + PG8_SA(b, h) + aoff + m * 2048 + k * 1024); } while (0)
; #define PG8_LDB(dst, b, h) do { _Pragma("unroll") for (int n = 0; n < 2; ++n) _Pragma("unroll") for (int k = 0; k < 2; ++k) dst[n][k] = *(const LAS bf16x8*)(lds + PG8_SB(b, h) + boff + n * 2048 + k * 1024); } while (0)
; #define PG8_WAIT_V(n) asm volatile("s_waitcnt vmcnt(" #n ")" ::: "memory")
; #define PG8_WAIT_L(n) asm volatile("s_waitcnt lgkmcnt(" #n ")" ::: "memory")
; #define PG8_BAR __builtin_amdgcn_s_barrier()
; #define PG8_SCHED __builtin_amdgcn_sched_barrier(0)
; template <class Epi, bool ALIGN_EPI = PG8_ALIGN, bool SP2 = PG8_SP2>
; __device__ __forceinline__ void gemm_phase(LAS unsigned char* lds, const Gemm g, const StaticOrder& S, const Epi& E) {
;     ...
;         const bool has_next = S.next(ui + 1, nxt);
;         const char* nA = has_next ? (const char*)g.A + (size_t)nxt.pm * tstepA : cA; const char* nB = has_next ? (const char*)g.Bt + (size_t)nxt.pn * tstepB : cB;
;         for (int t = 0; t < nt; t += 2) {
;             const bool last = (t == nt - 2);
;             const char* a1 = cA + (size_t)(t + 1) * kstepA;
;             const char* a2 = last ? nA : cA + (size_t)(t + 2) * kstepA; const char* b2 = last ? nB : cB + (size_t)(t + 2) * kstepB;
;             const char* a3 = a2 + kstepA; const char* b3 = b2 + kstepB;
;             if constexpr (SP2) {
;             PG8_LDB(B0, 0, 0); PG8_LDB(B1, 0, 1); PG8_SCHED; PG8_LDA(At, 0, 0); PG8_STAGE(PG8_SA(1, 1), a1 + hstepA, voffA);
;             PG8_WAIT_V(8); PG8_WAIT_L(0); PG8_BAR; PG8_MMA(0, 0, At, B0); PG8_MMA(0, 1, At, B1); PG8_BAR; PG8_SCHED;
;             PG8_LDA(At, 0, 1); PG8_STAGE(PG8_SB(0, 0), b2, voffB); PG8_STAGE(PG8_SB(0, 1), b2 + hstepB, voffB); PG8_STAGE(PG8_SA(0, 0), a2, voffA);
;             PG8_WAIT_V(8); PG8_WAIT_L(0); PG8_BAR; PG8_MMA(1, 0, At, B0); PG8_MMA(1, 1, At, B1); PG8_BAR; PG8_SCHED;
.LBB0_610:
	s_ashr_i32 s13, s12, 31
	s_lshl_b64 s[14:15], s[12:13], 19
	v_readlane_b32 s16, v252, 58
	v_readlane_b32 s17, v252, 59
	s_add_u32 s14, s16, s14
	s_addc_u32 s15, s17, s15
	s_and_b64 s[16:17], s[0:1], exec
	s_cselect_b32 s13, s15, s21
	s_cselect_b32 s43, s14, s20
	s_ashr_i32 s11, s10, 31
	s_lshl_b64 s[16:17], s[10:11], 19
	s_add_u32 s16, s30, s16
	s_addc_u32 s17, s31, s17
	s_and_b64 s[24:25], s[0:1], exec
	s_cselect_b32 s11, s17, s23
	s_cselect_b32 s44, s16, s22
	s_add_u32 s20, s20, 0x40080
	s_addc_u32 s21, s21, 0
	s_add_u32 s45, s22, 0x100
	s_addc_u32 s46, s23, 0
	s_mov_b32 s47, -2
.LBB0_611:
	s_cmp_eq_u32 s47, -2
	s_cbranch_scc1 .Lfirst_iter_u611
	s_add_u32 s22, s20, 0xfffc0080
	s_addc_u32 s23, s21, -1
	s_add_i32 s48, 0, 0x10000
	s_cmp_eq_u32 s47, 12
	s_cselect_b32 s25, s13, s23
	s_cselect_b32 s24, s43, s22
	v_add_u32_e32 v0, s48, v141
	s_cselect_b32 s23, s11, s46
	s_cselect_b32 s22, s44, s45
	s_add_i32 s52, 0, 0x14000
	ds_read_b128 v[144:147], v0
	ds_read_b128 v[148:151], v0 offset:1024
	ds_read_b128 v[152:155], v0 offset:2048
	ds_read_b128 v[156:159], v0 offset:3072
	v_add_u32_e32 v0, s52, v141
	ds_read_b128 v[170:173], v0
	ds_read_b128 v[174:177], v0 offset:1024
	ds_read_b128 v[178:181], v0 offset:2048
	ds_read_b128 v[182:185], v0 offset:3072
	v_lshl_add_u64 v[160:161], s[20:21], 0, v[134:135]
	s_add_i32 m0, s34, 0xc000
	ds_read_b128 v[186:189], v142
	ds_read_b128 v[206:209], v142 offset:1024
	ds_read_b128 v[210:213], v142 offset:2048
	ds_read_b128 v[214:217], v142 offset:3072
	ds_read_b128 v[218:221], v142 offset:4096
	ds_read_b128 v[222:225], v142 offset:5120
	ds_read_b128 v[226:229], v142 offset:6144
	ds_read_b128 v[230:233], v142 offset:7168
	global_load_lds_dwordx4 v[160:161], off
	v_lshl_add_u64 v[160:161], s[20:21], 0, v[136:137]
	s_add_i32 m0, s34, 0xe000
	s_nop 0
	global_load_lds_dwordx4 v[160:161], off
	s_waitcnt vmcnt(8)
	s_waitcnt lgkmcnt(0)
	s_barrier
	s_setprio 1
	s_waitcnt lgkmcnt(0)
	v_mfma_f32_16x16x32_bf16 v[126:129], v[144:147], v[186:189], v[126:129]
	v_mfma_f32_16x16x32_bf16 v[118:121], v[152:155], v[186:189], v[118:121]
	v_mfma_f32_16x16x32_bf16 v[110:113], v[144:147], v[210:213], v[110:113]
	v_mfma_f32_16x16x32_bf16 v[102:105], v[152:155], v[210:213], v[102:105]
	v_mfma_f32_16x16x32_bf16 v[94:97], v[144:147], v[218:221], v[94:97]
	v_mfma_f32_16x16x32_bf16 v[86:89], v[152:155], v[218:221], v[86:89]
	v_mfma_f32_16x16x32_bf16 v[78:81], v[144:147], v[226:229], v[78:81]
	v_mfma_f32_16x16x32_bf16 v[70:73], v[152:155], v[226:229], v[70:73]
	v_mfma_f32_16x16x32_bf16 v[126:129], v[148:151], v[206:209], v[126:129]
	v_mfma_f32_16x16x32_bf16 v[118:121], v[156:159], v[206:209], v[118:121]
	v_mfma_f32_16x16x32_bf16 v[110:113], v[148:151], v[214:217], v[110:113]
	v_mfma_f32_16x16x32_bf16 v[102:105], v[156:159], v[214:217], v[102:105]
	v_mfma_f32_16x16x32_bf16 v[94:97], v[148:151], v[222:225], v[94:97]
	v_mfma_f32_16x16x32_bf16 v[86:89], v[156:159], v[222:225], v[86:89]
	v_mfma_f32_16x16x32_bf16 v[78:81], v[148:151], v[230:233], v[78:81]
	v_mfma_f32_16x16x32_bf16 v[70:73], v[156:159], v[230:233], v[70:73]
	s_setprio 0
	s_setprio 1
	v_mfma_f32_16x16x32_bf16 v[122:125], v[170:173], v[186:189], v[122:125]
	v_mfma_f32_16x16x32_bf16 v[114:117], v[178:181], v[186:189], v[114:117]
	v_mfma_f32_16x16x32_bf16 v[106:109], v[170:173], v[210:213], v[106:109]
	v_mfma_f32_16x16x32_bf16 v[98:101], v[178:181], v[210:213], v[98:101]
	v_mfma_f32_16x16x32_bf16 v[90:93], v[170:173], v[218:221], v[90:93]
	v_mfma_f32_16x16x32_bf16 v[82:85], v[178:181], v[218:221], v[82:85]
	v_mfma_f32_16x16x32_bf16 v[74:77], v[170:173], v[226:229], v[74:77]
	v_mfma_f32_16x16x32_bf16 v[66:69], v[178:181], v[226:229], v[66:69]
	v_mfma_f32_16x16x32_bf16 v[122:125], v[174:177], v[206:209], v[122:125]
	v_mfma_f32_16x16x32_bf16 v[114:117], v[182:185], v[206:209], v[114:117]
	v_mfma_f32_16x16x32_bf16 v[106:109], v[174:177], v[214:217], v[106:109]
	v_mfma_f32_16x16x32_bf16 v[98:101], v[182:185], v[214:217], v[98:101]
	v_mfma_f32_16x16x32_bf16 v[90:93], v[174:177], v[222:225], v[90:93]
	v_mfma_f32_16x16x32_bf16 v[82:85], v[182:185], v[222:225], v[82:85]
	v_mfma_f32_16x16x32_bf16 v[74:77], v[174:177], v[230:233], v[74:77]
	v_mfma_f32_16x16x32_bf16 v[66:69], v[182:185], v[230:233], v[66:69]
	s_setprio 0
	s_barrier
	s_add_i32 s48, s48, s33
	v_lshl_add_u64 v[160:161], s[22:23], 0, v[130:131]
	s_mov_b32 m0, s48
	ds_read_b128 v[186:189], v142 offset:16384
	ds_read_b128 v[206:209], v142 offset:17408
	ds_read_b128 v[210:213], v142 offset:18432
	ds_read_b128 v[214:217], v142 offset:19456
	ds_read_b128 v[218:221], v142 offset:20480
	ds_read_b128 v[222:225], v142 offset:21504
	ds_read_b128 v[226:229], v142 offset:22528
	ds_read_b128 v[230:233], v142 offset:23552
	global_load_lds_dwordx4 v[160:161], off
	s_add_i32 m0, s48, 0x2000
	s_add_u32 s48, s22, 0x40000
	v_lshl_add_u64 v[164:165], s[22:23], 0, v[132:133]
	s_addc_u32 s49, s23, 0
	s_add_i32 s52, s52, s33
	global_load_lds_dwordx4 v[164:165], off
	v_lshl_add_u64 v[166:167], s[48:49], 0, v[130:131]
	s_mov_b32 m0, s52
	v_lshl_add_u64 v[194:195], s[24:25], 0, v[132:133]
	global_load_lds_dwordx4 v[166:167], off
	v_lshl_add_u64 v[166:167], s[48:49], 0, v[132:133]
	s_add_i32 m0, s52, 0x2000
	s_nop 0
	global_load_lds_dwordx4 v[166:167], off
	v_lshl_add_u64 v[166:167], s[24:25], 0, v[130:131]
	s_mov_b32 m0, s34
	s_nop 0
	global_load_lds_dwordx4 v[166:167], off
	s_mov_b32 m0, s35
	s_nop 0
	global_load_lds_dwordx4 v[194:195], off
	s_waitcnt vmcnt(8)
	s_waitcnt lgkmcnt(0)
	s_barrier
; #define PG8_STAGE(bufoff, gbase, voff) do { _Pragma("unroll") for (int _i = 0; _i < 2; ++_i) \
;         __builtin_amdgcn_global_load_lds((const unsigned*)((const char*)(gbase) + (voff)[_i]), (LAS unsigned*)(lds + (bufoff) + ldsw + _i * 8192), 16, 0, 0); } while (0)
; #define PG8_LDA(dst, b, h) do { _Pragma("unroll") for (int m = 0; m < 4; ++m) _Pragma("unroll") for (int k = 0; k < 2; ++k) dst[m][k] = *(const LAS bf16x8*)(lds + PG8_SA(b, h) + aoff + m * 2048 + k * 1024); } while (0)
; #define PG8_LDB(dst, b, h) do { _Pragma("unroll") for (int n = 0; n < 2; ++n) _Pragma("unroll") for (int k = 0; k < 2; ++k) dst[n][k] = *(const LAS bf16x8*)(lds + PG8_SB(b, h) + boff + n * 2048 + k * 1024); } while (0)
; #define PG8_MMA(ai, bj, At, Bt) do { __builtin_amdgcn_s_setprio(1); _Pragma("unroll") for (int m = 0; m < 4; ++m) _Pragma("unroll") for (int n = 0; n < 2; ++n) _Pragma("unroll") for (int k = 0; k < 2; ++k) \
;         acc[ai][bj][m][n] = __builtin_amdgcn_mfma_f32_16x16x32_bf16(Bt[n][k], At[m][k], acc[ai][bj][m][n], 0, 0, 0); __builtin_amdgcn_s_setprio(0); } while (0)
; #define PG8_WAIT_V(n) asm volatile("s_waitcnt vmcnt(" #n ")" ::: "memory")
; #define PG8_WAIT_L(n) asm volatile("s_waitcnt lgkmcnt(" #n ")" ::: "memory")
; #define PG8_BAR __builtin_amdgcn_s_barrier()
; #define PG8_SCHED __builtin_amdgcn_sched_barrier(0)
; template <class Epi, bool ALIGN_EPI = PG8_ALIGN, bool SP2 = PG8_SP2>
; __device__ __forceinline__ void gemm_phase(LAS unsigned char* lds, const Gemm g, const StaticOrder& S, const Epi& E) {
;     ...
;             PG8_WAIT_V(8); PG8_WAIT_L(0); PG8_BAR; PG8_MMA(1, 0, At, B0); PG8_MMA(1, 1, At, B1); PG8_BAR; PG8_SCHED;
;             PG8_LDB(B0, 1, 0); PG8_LDB(B1, 1, 1); PG8_SCHED; PG8_LDA(At, 1, 0); PG8_STAGE(PG8_SA(0, 1), a2 + hstepA, voffA);
;             PG8_WAIT_V(8); PG8_WAIT_L(0); PG8_BAR; PG8_MMA(0, 0, At, B0); PG8_MMA(0, 1, At, B1); PG8_BAR; PG8_SCHED;
;             PG8_LDA(At, 1, 1); PG8_STAGE(PG8_SB(1, 0), b3, voffB); PG8_STAGE(PG8_SB(1, 1), b3 + hstepB, voffB); PG8_STAGE(PG8_SA(1, 0), a3, voffA);
	s_setprio 1
	s_waitcnt lgkmcnt(0)
	v_mfma_f32_16x16x32_bf16 v[62:65], v[144:147], v[186:189], v[62:65]
	v_mfma_f32_16x16x32_bf16 v[54:57], v[152:155], v[186:189], v[54:57]
	v_mfma_f32_16x16x32_bf16 v[46:49], v[144:147], v[210:213], v[46:49]
	v_mfma_f32_16x16x32_bf16 v[38:41], v[152:155], v[210:213], v[38:41]
	v_mfma_f32_16x16x32_bf16 v[30:33], v[144:147], v[218:221], v[30:33]
	v_mfma_f32_16x16x32_bf16 v[22:25], v[152:155], v[218:221], v[22:25]
	v_mfma_f32_16x16x32_bf16 v[14:17], v[144:147], v[226:229], v[14:17]
	v_mfma_f32_16x16x32_bf16 v[6:9], v[152:155], v[226:229], v[6:9]
	v_mfma_f32_16x16x32_bf16 v[62:65], v[148:151], v[206:209], v[62:65]
	v_mfma_f32_16x16x32_bf16 v[54:57], v[156:159], v[206:209], v[54:57]
	v_mfma_f32_16x16x32_bf16 v[46:49], v[148:151], v[214:217], v[46:49]
	v_mfma_f32_16x16x32_bf16 v[38:41], v[156:159], v[214:217], v[38:41]
	v_mfma_f32_16x16x32_bf16 v[30:33], v[148:151], v[222:225], v[30:33]
	v_mfma_f32_16x16x32_bf16 v[22:25], v[156:159], v[222:225], v[22:25]
	v_mfma_f32_16x16x32_bf16 v[14:17], v[148:151], v[230:233], v[14:17]
	v_mfma_f32_16x16x32_bf16 v[6:9], v[156:159], v[230:233], v[6:9]
	s_setprio 0
	s_setprio 1
	v_mfma_f32_16x16x32_bf16 v[58:61], v[170:173], v[186:189], v[58:61]
	v_mfma_f32_16x16x32_bf16 v[50:53], v[178:181], v[186:189], v[50:53]
	v_mfma_f32_16x16x32_bf16 v[42:45], v[170:173], v[210:213], v[42:45]
	v_mfma_f32_16x16x32_bf16 v[34:37], v[178:181], v[210:213], v[34:37]
	v_mfma_f32_16x16x32_bf16 v[26:29], v[170:173], v[218:221], v[26:29]
	v_mfma_f32_16x16x32_bf16 v[18:21], v[178:181], v[218:221], v[18:21]
	v_mfma_f32_16x16x32_bf16 v[10:13], v[170:173], v[226:229], v[10:13]
	v_mfma_f32_16x16x32_bf16 v[2:5], v[178:181], v[226:229], v[2:5]
	v_mfma_f32_16x16x32_bf16 v[58:61], v[174:177], v[206:209], v[58:61]
	v_mfma_f32_16x16x32_bf16 v[50:53], v[182:185], v[206:209], v[50:53]
	v_mfma_f32_16x16x32_bf16 v[42:45], v[174:177], v[214:217], v[42:45]
	v_mfma_f32_16x16x32_bf16 v[34:37], v[182:185], v[214:217], v[34:37]
	v_mfma_f32_16x16x32_bf16 v[26:29], v[174:177], v[222:225], v[26:29]
	v_mfma_f32_16x16x32_bf16 v[18:21], v[182:185], v[222:225], v[18:21]
	v_mfma_f32_16x16x32_bf16 v[10:13], v[174:177], v[230:233], v[10:13]
	v_mfma_f32_16x16x32_bf16 v[2:5], v[182:185], v[230:233], v[2:5]
	s_setprio 0
	s_barrier
	s_add_i32 s48, 0, 0x18000
	v_add_u32_e32 v0, s48, v141
	s_add_i32 s49, 0, 0x1c000
	ds_read_b128 v[144:147], v0
	ds_read_b128 v[148:151], v0 offset:1024
	ds_read_b128 v[152:155], v0 offset:2048
	ds_read_b128 v[156:159], v0 offset:3072
	v_add_u32_e32 v0, s49, v141
	ds_read_b128 v[170:173], v0
	ds_read_b128 v[174:177], v0 offset:1024
	ds_read_b128 v[178:181], v0 offset:2048
	ds_read_b128 v[182:185], v0 offset:3072
	s_add_u32 s24, s24, 0x40000
	s_addc_u32 s25, s25, 0
	s_mov_b32 m0, s36
	v_lshl_add_u64 v[196:197], s[24:25], 0, v[130:131]
	ds_read_b128 v[186:189], v142 offset:32768
	ds_read_b128 v[206:209], v142 offset:33792
	ds_read_b128 v[210:213], v142 offset:34816
	ds_read_b128 v[214:217], v142 offset:35840
	ds_read_b128 v[218:221], v142 offset:36864
	ds_read_b128 v[222:225], v142 offset:37888
	ds_read_b128 v[226:229], v142 offset:38912
	ds_read_b128 v[230:233], v142 offset:39936
	global_load_lds_dwordx4 v[196:197], off
	v_lshl_add_u64 v[196:197], s[24:25], 0, v[132:133]
	s_mov_b32 m0, s37
	s_nop 0
	global_load_lds_dwordx4 v[196:197], off
	s_waitcnt vmcnt(8)
	s_waitcnt lgkmcnt(0)
	s_barrier
	s_setprio 1
	s_waitcnt lgkmcnt(0)
	v_mfma_f32_16x16x32_bf16 v[126:129], v[144:147], v[186:189], v[126:129]
	v_mfma_f32_16x16x32_bf16 v[118:121], v[152:155], v[186:189], v[118:121]
	v_mfma_f32_16x16x32_bf16 v[110:113], v[144:147], v[210:213], v[110:113]
	v_mfma_f32_16x16x32_bf16 v[102:105], v[152:155], v[210:213], v[102:105]
	v_mfma_f32_16x16x32_bf16 v[94:97], v[144:147], v[218:221], v[94:97]
	v_mfma_f32_16x16x32_bf16 v[86:89], v[152:155], v[218:221], v[86:89]
	v_mfma_f32_16x16x32_bf16 v[78:81], v[144:147], v[226:229], v[78:81]
	v_mfma_f32_16x16x32_bf16 v[70:73], v[152:155], v[226:229], v[70:73]
	v_mfma_f32_16x16x32_bf16 v[126:129], v[148:151], v[206:209], v[126:129]
	v_mfma_f32_16x16x32_bf16 v[118:121], v[156:159], v[206:209], v[118:121]
	v_mfma_f32_16x16x32_bf16 v[110:113], v[148:151], v[214:217], v[110:113]
	v_mfma_f32_16x16x32_bf16 v[102:105], v[156:159], v[214:217], v[102:105]
	v_mfma_f32_16x16x32_bf16 v[94:97], v[148:151], v[222:225], v[94:97]
	v_mfma_f32_16x16x32_bf16 v[86:89], v[156:159], v[222:225], v[86:89]
	v_mfma_f32_16x16x32_bf16 v[78:81], v[148:151], v[230:233], v[78:81]
	v_mfma_f32_16x16x32_bf16 v[70:73], v[156:159], v[230:233], v[70:73]
	s_setprio 0
	s_setprio 1
	v_mfma_f32_16x16x32_bf16 v[122:125], v[170:173], v[186:189], v[122:125]
	v_mfma_f32_16x16x32_bf16 v[114:117], v[178:181], v[186:189], v[114:117]
	v_mfma_f32_16x16x32_bf16 v[106:109], v[170:173], v[210:213], v[106:109]
	v_mfma_f32_16x16x32_bf16 v[98:101], v[178:181], v[210:213], v[98:101]
	v_mfma_f32_16x16x32_bf16 v[90:93], v[170:173], v[218:221], v[90:93]
	v_mfma_f32_16x16x32_bf16 v[82:85], v[178:181], v[218:221], v[82:85]
	v_mfma_f32_16x16x32_bf16 v[74:77], v[170:173], v[226:229], v[74:77]
	v_mfma_f32_16x16x32_bf16 v[66:69], v[178:181], v[226:229], v[66:69]
	v_mfma_f32_16x16x32_bf16 v[122:125], v[174:177], v[206:209], v[122:125]
	v_mfma_f32_16x16x32_bf16 v[114:117], v[182:185], v[206:209], v[114:117]
	v_mfma_f32_16x16x32_bf16 v[106:109], v[174:177], v[214:217], v[106:109]
	v_mfma_f32_16x16x32_bf16 v[98:101], v[182:185], v[214:217], v[98:101]
	v_mfma_f32_16x16x32_bf16 v[90:93], v[174:177], v[222:225], v[90:93]
	v_mfma_f32_16x16x32_bf16 v[82:85], v[182:185], v[222:225], v[82:85]
	v_mfma_f32_16x16x32_bf16 v[74:77], v[174:177], v[230:233], v[74:77]
	v_mfma_f32_16x16x32_bf16 v[66:69], v[182:185], v[230:233], v[66:69]
	s_setprio 0
	s_barrier
; #define PG8_STAGE(bufoff, gbase, voff) do { _Pragma("unroll") for (int _i = 0; _i < 2; ++_i) \
;         __builtin_amdgcn_global_load_lds((const unsigned*)((const char*)(gbase) + (voff)[_i]), (LAS unsigned*)(lds + (bufoff) + ldsw + _i * 8192), 16, 0, 0); } while (0)
; #define PG8_LDA(dst, b, h) do { _Pragma("unroll") for (int m = 0; m < 4; ++m) _Pragma("unroll") for (int k = 0; k < 2; ++k) dst[m][k] = *(const LAS bf16x8*)(lds + PG8_SA(b, h) + aoff + m * 2048 + k * 1024); } while (0)
; #define PG8_MMA(ai, bj, At, Bt) do { __builtin_amdgcn_s_setprio(1); _Pragma("unroll") for (int m = 0; m < 4; ++m) _Pragma("unroll") for (int n = 0; n < 2; ++n) _Pragma("unroll") for (int k = 0; k < 2; ++k) \
;         acc[ai][bj][m][n] = __builtin_amdgcn_mfma_f32_16x16x32_bf16(Bt[n][k], At[m][k], acc[ai][bj][m][n], 0, 0, 0); __builtin_amdgcn_s_setprio(0); } while (0)
; #define PG8_WAIT_V(n) asm volatile("s_waitcnt vmcnt(" #n ")" ::: "memory")
; #define PG8_WAIT_L(n) asm volatile("s_waitcnt lgkmcnt(" #n ")" ::: "memory")
; #define PG8_BAR __builtin_amdgcn_s_barrier()
; #define PG8_SCHED __builtin_amdgcn_sched_barrier(0)
; template <class Epi, bool ALIGN_EPI = PG8_ALIGN, bool SP2 = PG8_SP2>
; __device__ __forceinline__ void gemm_phase(LAS unsigned char* lds, const Gemm g, const StaticOrder& S, const Epi& E) {
;     ...
;             PG8_WAIT_V(8); PG8_WAIT_L(0); PG8_BAR; PG8_MMA(0, 0, At, B0); PG8_MMA(0, 1, At, B1); PG8_BAR; PG8_SCHED;
;             PG8_LDA(At, 1, 1); PG8_STAGE(PG8_SB(1, 0), b3, voffB); PG8_STAGE(PG8_SB(1, 1), b3 + hstepB, voffB); PG8_STAGE(PG8_SA(1, 0), a3, voffA);
;             PG8_WAIT_V(8); PG8_WAIT_L(0); PG8_BAR; PG8_MMA(1, 0, At, B0); PG8_MMA(1, 1, At, B1); PG8_BAR; PG8_SCHED;
	s_add_i32 s24, s48, s33
	v_lshl_add_u64 v[160:161], v[160:161], 0, s[50:51]
	s_mov_b32 m0, s24
	ds_read_b128 v[186:189], v142 offset:49152
	ds_read_b128 v[206:209], v142 offset:50176
	ds_read_b128 v[210:213], v142 offset:51200
	ds_read_b128 v[214:217], v142 offset:52224
	ds_read_b128 v[218:221], v142 offset:53248
	ds_read_b128 v[222:225], v142 offset:54272
	ds_read_b128 v[226:229], v142 offset:55296
	ds_read_b128 v[230:233], v142 offset:56320
	global_load_lds_dwordx4 v[160:161], off
	s_add_i32 m0, s24, 0x2000
	s_add_u32 s22, s22, 0x40080
	v_lshl_add_u64 v[160:161], v[164:165], 0, s[50:51]
	s_addc_u32 s23, s23, 0
	s_add_i32 s24, s49, s33
	global_load_lds_dwordx4 v[160:161], off
	v_lshl_add_u64 v[160:161], s[22:23], 0, v[130:131]
	s_mov_b32 m0, s24
	s_nop 0
	global_load_lds_dwordx4 v[160:161], off
	v_lshl_add_u64 v[160:161], s[22:23], 0, v[132:133]
	s_add_i32 m0, s24, 0x2000
	s_nop 0
	global_load_lds_dwordx4 v[160:161], off
	v_lshl_add_u64 v[160:161], v[166:167], 0, s[50:51]
	s_mov_b32 m0, s40
	s_nop 0
	global_load_lds_dwordx4 v[160:161], off
	v_lshl_add_u64 v[160:161], v[194:195], 0, s[50:51]
	s_mov_b32 m0, s41
	s_nop 0
	global_load_lds_dwordx4 v[160:161], off
	s_waitcnt vmcnt(8)
	s_waitcnt lgkmcnt(0)
	s_barrier
	s_setprio 1
	s_waitcnt lgkmcnt(0)
	v_mfma_f32_16x16x32_bf16 v[62:65], v[144:147], v[186:189], v[62:65]
	v_mfma_f32_16x16x32_bf16 v[54:57], v[152:155], v[186:189], v[54:57]
	v_mfma_f32_16x16x32_bf16 v[46:49], v[144:147], v[210:213], v[46:49]
	v_mfma_f32_16x16x32_bf16 v[38:41], v[152:155], v[210:213], v[38:41]
	v_mfma_f32_16x16x32_bf16 v[30:33], v[144:147], v[218:221], v[30:33]
	v_mfma_f32_16x16x32_bf16 v[22:25], v[152:155], v[218:221], v[22:25]
	v_mfma_f32_16x16x32_bf16 v[14:17], v[144:147], v[226:229], v[14:17]
	v_mfma_f32_16x16x32_bf16 v[6:9], v[152:155], v[226:229], v[6:9]
	v_mfma_f32_16x16x32_bf16 v[62:65], v[148:151], v[206:209], v[62:65]
	v_mfma_f32_16x16x32_bf16 v[54:57], v[156:159], v[206:209], v[54:57]
	v_mfma_f32_16x16x32_bf16 v[46:49], v[148:151], v[214:217], v[46:49]
	v_mfma_f32_16x16x32_bf16 v[38:41], v[156:159], v[214:217], v[38:41]
	v_mfma_f32_16x16x32_bf16 v[30:33], v[148:151], v[222:225], v[30:33]
	v_mfma_f32_16x16x32_bf16 v[22:25], v[156:159], v[222:225], v[22:25]
	v_mfma_f32_16x16x32_bf16 v[14:17], v[148:151], v[230:233], v[14:17]
	v_mfma_f32_16x16x32_bf16 v[6:9], v[156:159], v[230:233], v[6:9]
	s_setprio 0
	s_setprio 1
	v_mfma_f32_16x16x32_bf16 v[58:61], v[170:173], v[186:189], v[58:61]
	v_mfma_f32_16x16x32_bf16 v[50:53], v[178:181], v[186:189], v[50:53]
	v_mfma_f32_16x16x32_bf16 v[42:45], v[170:173], v[210:213], v[42:45]
	v_mfma_f32_16x16x32_bf16 v[34:37], v[178:181], v[210:213], v[34:37]
	v_mfma_f32_16x16x32_bf16 v[26:29], v[170:173], v[218:221], v[26:29]
	v_mfma_f32_16x16x32_bf16 v[18:21], v[178:181], v[218:221], v[18:21]
	v_mfma_f32_16x16x32_bf16 v[10:13], v[170:173], v[226:229], v[10:13]
	v_mfma_f32_16x16x32_bf16 v[2:5], v[178:181], v[226:229], v[2:5]
	v_mfma_f32_16x16x32_bf16 v[58:61], v[174:177], v[206:209], v[58:61]
	v_mfma_f32_16x16x32_bf16 v[50:53], v[182:185], v[206:209], v[50:53]
	v_mfma_f32_16x16x32_bf16 v[42:45], v[174:177], v[214:217], v[42:45]
	v_mfma_f32_16x16x32_bf16 v[34:37], v[182:185], v[214:217], v[34:37]
	v_mfma_f32_16x16x32_bf16 v[26:29], v[174:177], v[222:225], v[26:29]
	v_mfma_f32_16x16x32_bf16 v[18:21], v[182:185], v[222:225], v[18:21]
	v_mfma_f32_16x16x32_bf16 v[10:13], v[174:177], v[230:233], v[10:13]
	v_mfma_f32_16x16x32_bf16 v[2:5], v[182:185], v[230:233], v[2:5]
	s_setprio 0
	s_barrier
	s_add_i32 s47, s47, 2
	s_add_u32 s20, s20, 0x100
	s_addc_u32 s21, s21, 0
	s_add_u32 s45, s45, 0x100
	s_addc_u32 s46, s46, 0
	s_cmp_gt_u32 s47, 13
	s_cbranch_scc0 .LBB0_611
	s_and_b64 vcc, exec, s[8:9]
	s_cbranch_vccz .LBB0_614
	s_barrier

; #define PG8_STAGE(bufoff, gbase, voff) do { _Pragma("unroll") for (int _i = 0; _i < 2; ++_i) \
;         __builtin_amdgcn_global_load_lds((const unsigned*)((const char*)(gbase) + (voff)[_i]), (LAS unsigned*)(lds + (bufoff) + ldsw + _i * 8192), 16, 0, 0); } while (0)
; #define PG8_LDA(dst, b, h) do { _Pragma("unroll") for (int m = 0; m < 4; ++m) _Pragma("unroll") for (int k = 0; k < 2; ++k) dst[m][k] = *(const LAS bf16x8*)(lds + PG8_SA(b, h) + aoff + m * 2048 + k * 1024); } while (0)
; #define PG8_LDB(dst, b, h) do { _Pragma("unroll") for (int n = 0; n < 2; ++n) _Pragma("unroll") for (int k = 0; k < 2; ++k) dst[n][k] = *(const LAS bf16x8*)(lds + PG8_SB(b, h) + boff + n * 2048 + k * 1024); } while (0)
; #define PG8_MMA(ai, bj, At, Bt) do { __builtin_amdgcn_s_setprio(1); _Pragma("unroll") for (int m = 0; m < 4; ++m) _Pragma("unroll") for (int n = 0; n < 2; ++n) _Pragma("unroll") for (int k = 0; k < 2; ++k) \
;         acc[ai][bj][m][n] = __builtin_amdgcn_mfma_f32_16x16x32_bf16(Bt[n][k], At[m][k], acc[ai][bj][m][n], 0, 0, 0); __builtin_amdgcn_s_setprio(0); } while (0)
; #define PG8_WAIT_V(n) asm volatile("s_waitcnt vmcnt(" #n ")" ::: "memory")
; #define PG8_WAIT_L(n) asm volatile("s_waitcnt lgkmcnt(" #n ")" ::: "memory")
; #define PG8_BAR __builtin_amdgcn_s_barrier()
; template <class Epi, bool ALIGN_EPI = PG8_ALIGN, bool SP2 = PG8_SP2>
; __device__ __forceinline__ void gemm_phase(LAS unsigned char* lds, const Gemm g, const StaticOrder& S, const Epi& E) {
;     ...
;         for (int t = 0; t < nt; t += 2) {
;             const bool last = (t == nt - 2);
;             const char* a1 = cA + (size_t)(t + 1) * kstepA;
;             const char* a2 = last ? nA : cA + (size_t)(t + 2) * kstepA; const char* b2 = last ? nB : cB + (size_t)(t + 2) * kstepB;
;             const char* a3 = a2 + kstepA; const char* b3 = b2 + kstepB;
;             if constexpr (SP2) {
;             PG8_LDB(B0, 0, 0); PG8_LDB(B1, 0, 1); PG8_SCHED; PG8_LDA(At, 0, 0); PG8_STAGE(PG8_SA(1, 1), a1 + hstepA, voffA);
;             PG8_WAIT_V(8); PG8_WAIT_L(0); PG8_BAR; PG8_MMA(0, 0, At, B0); PG8_MMA(0, 1, At, B1); PG8_BAR; PG8_SCHED;
;             PG8_LDA(At, 0, 1); PG8_STAGE(PG8_SB(0, 0), b2, voffB); PG8_STAGE(PG8_SB(0, 1), b2 + hstepB, voffB); PG8_STAGE(PG8_SA(0, 0), a2, voffA);
;             PG8_WAIT_V(8); PG8_WAIT_L(0); PG8_BAR; PG8_MMA(1, 0, At, B0); PG8_MMA(1, 1, At, B1); PG8_BAR; PG8_SCHED;
.Lfirst_iter_u611:
	s_add_u32 s22, s20, 0xfffc0080
	s_addc_u32 s23, s21, -1
	s_add_i32 s48, 0, 0x10000
	s_cmp_eq_u32 s47, 12
	s_cselect_b32 s25, s13, s23
	s_cselect_b32 s24, s43, s22
	v_add_u32_e32 v0, s48, v141
	s_cselect_b32 s23, s11, s46
	s_cselect_b32 s22, s44, s45
	s_add_i32 s52, 0, 0x14000
	ds_read_b128 v[144:147], v0
	ds_read_b128 v[148:151], v0 offset:1024
	ds_read_b128 v[152:155], v0 offset:2048
	ds_read_b128 v[156:159], v0 offset:3072
	v_add_u32_e32 v0, s52, v141
	ds_read_b128 v[170:173], v0
	ds_read_b128 v[174:177], v0 offset:1024
	ds_read_b128 v[178:181], v0 offset:2048
	ds_read_b128 v[182:185], v0 offset:3072
	v_lshl_add_u64 v[160:161], s[20:21], 0, v[134:135]
	s_add_i32 m0, s34, 0xc000
	ds_read_b128 v[186:189], v142
	ds_read_b128 v[206:209], v142 offset:1024
	ds_read_b128 v[210:213], v142 offset:2048
	ds_read_b128 v[214:217], v142 offset:3072
	ds_read_b128 v[218:221], v142 offset:4096
	ds_read_b128 v[222:225], v142 offset:5120
	ds_read_b128 v[226:229], v142 offset:6144
	ds_read_b128 v[230:233], v142 offset:7168
	global_load_lds_dwordx4 v[160:161], off
	v_lshl_add_u64 v[160:161], s[20:21], 0, v[136:137]
	s_add_i32 m0, s34, 0xe000
	s_nop 0
	global_load_lds_dwordx4 v[160:161], off
	s_waitcnt vmcnt(8)
	s_waitcnt lgkmcnt(0)
	s_barrier
	s_setprio 1
	s_waitcnt lgkmcnt(0)
	v_mfma_f32_16x16x32_bf16 v[126:129], v[144:147], v[186:189], 0
	v_mfma_f32_16x16x32_bf16 v[118:121], v[152:155], v[186:189], 0
	v_mfma_f32_16x16x32_bf16 v[110:113], v[144:147], v[210:213], 0
	v_mfma_f32_16x16x32_bf16 v[102:105], v[152:155], v[210:213], 0
	v_mfma_f32_16x16x32_bf16 v[94:97], v[144:147], v[218:221], 0
	v_mfma_f32_16x16x32_bf16 v[86:89], v[152:155], v[218:221], 0
	v_mfma_f32_16x16x32_bf16 v[78:81], v[144:147], v[226:229], 0
	v_mfma_f32_16x16x32_bf16 v[70:73], v[152:155], v[226:229], 0
	v_mfma_f32_16x16x32_bf16 v[126:129], v[148:151], v[206:209], v[126:129]
	v_mfma_f32_16x16x32_bf16 v[118:121], v[156:159], v[206:209], v[118:121]
	v_mfma_f32_16x16x32_bf16 v[110:113], v[148:151], v[214:217], v[110:113]
	v_mfma_f32_16x16x32_bf16 v[102:105], v[156:159], v[214:217], v[102:105]
	v_mfma_f32_16x16x32_bf16 v[94:97], v[148:151], v[222:225], v[94:97]
	v_mfma_f32_16x16x32_bf16 v[86:89], v[156:159], v[222:225], v[86:89]
	v_mfma_f32_16x16x32_bf16 v[78:81], v[148:151], v[230:233], v[78:81]
	v_mfma_f32_16x16x32_bf16 v[70:73], v[156:159], v[230:233], v[70:73]
	s_setprio 0
	s_setprio 1
	v_mfma_f32_16x16x32_bf16 v[122:125], v[170:173], v[186:189], 0
	v_mfma_f32_16x16x32_bf16 v[114:117], v[178:181], v[186:189], 0
	v_mfma_f32_16x16x32_bf16 v[106:109], v[170:173], v[210:213], 0
	v_mfma_f32_16x16x32_bf16 v[98:101], v[178:181], v[210:213], 0
	v_mfma_f32_16x16x32_bf16 v[90:93], v[170:173], v[218:221], 0
	v_mfma_f32_16x16x32_bf16 v[82:85], v[178:181], v[218:221], 0
	v_mfma_f32_16x16x32_bf16 v[74:77], v[170:173], v[226:229], 0
	v_mfma_f32_16x16x32_bf16 v[66:69], v[178:181], v[226:229], 0
	v_mfma_f32_16x16x32_bf16 v[122:125], v[174:177], v[206:209], v[122:125]
	v_mfma_f32_16x16x32_bf16 v[114:117], v[182:185], v[206:209], v[114:117]
	v_mfma_f32_16x16x32_bf16 v[106:109], v[174:177], v[214:217], v[106:109]
	v_mfma_f32_16x16x32_bf16 v[98:101], v[182:185], v[214:217], v[98:101]
	v_mfma_f32_16x16x32_bf16 v[90:93], v[174:177], v[222:225], v[90:93]
	v_mfma_f32_16x16x32_bf16 v[82:85], v[182:185], v[222:225], v[82:85]
	v_mfma_f32_16x16x32_bf16 v[74:77], v[174:177], v[230:233], v[74:77]
	v_mfma_f32_16x16x32_bf16 v[66:69], v[182:185], v[230:233], v[66:69]
	s_setprio 0
	s_barrier
	s_add_i32 s48, s48, s33
	v_lshl_add_u64 v[160:161], s[22:23], 0, v[130:131]
	s_mov_b32 m0, s48
	ds_read_b128 v[186:189], v142 offset:16384
	ds_read_b128 v[206:209], v142 offset:17408
	ds_read_b128 v[210:213], v142 offset:18432
	ds_read_b128 v[214:217], v142 offset:19456
	ds_read_b128 v[218:221], v142 offset:20480
	ds_read_b128 v[222:225], v142 offset:21504
	ds_read_b128 v[226:229], v142 offset:22528
	ds_read_b128 v[230:233], v142 offset:23552
	global_load_lds_dwordx4 v[160:161], off
	s_add_i32 m0, s48, 0x2000
	s_add_u32 s48, s22, 0x40000
	v_lshl_add_u64 v[164:165], s[22:23], 0, v[132:133]
	s_addc_u32 s49, s23, 0
	s_add_i32 s52, s52, s33
	global_load_lds_dwordx4 v[164:165], off
	v_lshl_add_u64 v[166:167], s[48:49], 0, v[130:131]
	s_mov_b32 m0, s52
	v_lshl_add_u64 v[194:195], s[24:25], 0, v[132:133]
	global_load_lds_dwordx4 v[166:167], off
	v_lshl_add_u64 v[166:167], s[48:49], 0, v[132:133]
	s_add_i32 m0, s52, 0x2000
	s_nop 0
	global_load_lds_dwordx4 v[166:167], off
	v_lshl_add_u64 v[166:167], s[24:25], 0, v[130:131]
	s_mov_b32 m0, s34
	s_nop 0
	global_load_lds_dwordx4 v[166:167], off
	s_mov_b32 m0, s35
	s_nop 0
	global_load_lds_dwordx4 v[194:195], off
	s_waitcnt vmcnt(8)
	s_waitcnt lgkmcnt(0)
	s_barrier
; #define PG8_STAGE(bufoff, gbase, voff) do { _Pragma("unroll") for (int _i = 0; _i < 2; ++_i) \
;         __builtin_amdgcn_global_load_lds((const unsigned*)((const char*)(gbase) + (voff)[_i]), (LAS unsigned*)(lds + (bufoff) + ldsw + _i * 8192), 16, 0, 0); } while (0)
; #define PG8_LDA(dst, b, h) do { _Pragma("unroll") for (int m = 0; m < 4; ++m) _Pragma("unroll") for (int k = 0; k < 2; ++k) dst[m][k] = *(const LAS bf16x8*)(lds + PG8_SA(b, h) + aoff + m * 2048 + k * 1024); } while (0)
; #define PG8_LDB(dst, b, h) do { _Pragma("unroll") for (int n = 0; n < 2; ++n) _Pragma("unroll") for (int k = 0; k < 2; ++k) dst[n][k] = *(const LAS bf16x8*)(lds + PG8_SB(b, h) + boff + n * 2048 + k * 1024); } while (0)
; #define PG8_MMA(ai, bj, At, Bt) do { __builtin_amdgcn_s_setprio(1); _Pragma("unroll") for (int m = 0; m < 4; ++m) _Pragma("unroll") for (int n = 0; n < 2; ++n) _Pragma("unroll") for (int k = 0; k < 2; ++k) \
;         acc[ai][bj][m][n] = __builtin_amdgcn_mfma_f32_16x16x32_bf16(Bt[n][k], At[m][k], acc[ai][bj][m][n], 0, 0, 0); __builtin_amdgcn_s_setprio(0); } while (0)
; #define PG8_WAIT_V(n) asm volatile("s_waitcnt vmcnt(" #n ")" ::: "memory")
; #define PG8_WAIT_L(n) asm volatile("s_waitcnt lgkmcnt(" #n ")" ::: "memory")
; #define PG8_BAR __builtin_amdgcn_s_barrier()
; #define PG8_SCHED __builtin_amdgcn_sched_barrier(0)
; template <class Epi, bool ALIGN_EPI = PG8_ALIGN, bool SP2 = PG8_SP2>
; __device__ __forceinline__ void gemm_phase(LAS unsigned char* lds, const Gemm g, const StaticOrder& S, const Epi& E) {
;     ...
;             PG8_WAIT_V(8); PG8_WAIT_L(0); PG8_BAR; PG8_MMA(1, 0, At, B0); PG8_MMA(1, 1, At, B1); PG8_BAR; PG8_SCHED;
;             PG8_LDB(B0, 1, 0); PG8_LDB(B1, 1, 1); PG8_SCHED; PG8_LDA(At, 1, 0); PG8_STAGE(PG8_SA(0, 1), a2 + hstepA, voffA);
;             PG8_WAIT_V(8); PG8_WAIT_L(0); PG8_BAR; PG8_MMA(0, 0, At, B0); PG8_MMA(0, 1, At, B1); PG8_BAR; PG8_SCHED;
;             PG8_LDA(At, 1, 1); PG8_STAGE(PG8_SB(1, 0), b3, voffB); PG8_STAGE(PG8_SB(1, 1), b3 + hstepB, voffB); PG8_STAGE(PG8_SA(1, 0), a3, voffA);
	s_setprio 1
	s_waitcnt lgkmcnt(0)
	v_mfma_f32_16x16x32_bf16 v[62:65], v[144:147], v[186:189], 0
	v_mfma_f32_16x16x32_bf16 v[54:57], v[152:155], v[186:189], 0
	v_mfma_f32_16x16x32_bf16 v[46:49], v[144:147], v[210:213], 0
	v_mfma_f32_16x16x32_bf16 v[38:41], v[152:155], v[210:213], 0
	v_mfma_f32_16x16x32_bf16 v[30:33], v[144:147], v[218:221], 0
	v_mfma_f32_16x16x32_bf16 v[22:25], v[152:155], v[218:221], 0
	v_mfma_f32_16x16x32_bf16 v[14:17], v[144:147], v[226:229], 0
	v_mfma_f32_16x16x32_bf16 v[6:9], v[152:155], v[226:229], 0
	v_mfma_f32_16x16x32_bf16 v[62:65], v[148:151], v[206:209], v[62:65]
	v_mfma_f32_16x16x32_bf16 v[54:57], v[156:159], v[206:209], v[54:57]
	v_mfma_f32_16x16x32_bf16 v[46:49], v[148:151], v[214:217], v[46:49]
	v_mfma_f32_16x16x32_bf16 v[38:41], v[156:159], v[214:217], v[38:41]
	v_mfma_f32_16x16x32_bf16 v[30:33], v[148:151], v[222:225], v[30:33]
	v_mfma_f32_16x16x32_bf16 v[22:25], v[156:159], v[222:225], v[22:25]
	v_mfma_f32_16x16x32_bf16 v[14:17], v[148:151], v[230:233], v[14:17]
	v_mfma_f32_16x16x32_bf16 v[6:9], v[156:159], v[230:233], v[6:9]
	s_setprio 0
	s_setprio 1
	v_mfma_f32_16x16x32_bf16 v[58:61], v[170:173], v[186:189], 0
	v_mfma_f32_16x16x32_bf16 v[50:53], v[178:181], v[186:189], 0
	v_mfma_f32_16x16x32_bf16 v[42:45], v[170:173], v[210:213], 0
	v_mfma_f32_16x16x32_bf16 v[34:37], v[178:181], v[210:213], 0
	v_mfma_f32_16x16x32_bf16 v[26:29], v[170:173], v[218:221], 0
	v_mfma_f32_16x16x32_bf16 v[18:21], v[178:181], v[218:221], 0
	v_mfma_f32_16x16x32_bf16 v[10:13], v[170:173], v[226:229], 0
	v_mfma_f32_16x16x32_bf16 v[2:5], v[178:181], v[226:229], 0
	v_mfma_f32_16x16x32_bf16 v[58:61], v[174:177], v[206:209], v[58:61]
	v_mfma_f32_16x16x32_bf16 v[50:53], v[182:185], v[206:209], v[50:53]
	v_mfma_f32_16x16x32_bf16 v[42:45], v[174:177], v[214:217], v[42:45]
	v_mfma_f32_16x16x32_bf16 v[34:37], v[182:185], v[214:217], v[34:37]
	v_mfma_f32_16x16x32_bf16 v[26:29], v[174:177], v[222:225], v[26:29]
	v_mfma_f32_16x16x32_bf16 v[18:21], v[182:185], v[222:225], v[18:21]
	v_mfma_f32_16x16x32_bf16 v[10:13], v[174:177], v[230:233], v[10:13]
	v_mfma_f32_16x16x32_bf16 v[2:5], v[182:185], v[230:233], v[2:5]
	s_setprio 0
	s_barrier
	s_add_i32 s48, 0, 0x18000
	v_add_u32_e32 v0, s48, v141
	s_add_i32 s49, 0, 0x1c000
	ds_read_b128 v[144:147], v0
	ds_read_b128 v[148:151], v0 offset:1024
	ds_read_b128 v[152:155], v0 offset:2048
	ds_read_b128 v[156:159], v0 offset:3072
	v_add_u32_e32 v0, s49, v141
	ds_read_b128 v[170:173], v0
	ds_read_b128 v[174:177], v0 offset:1024
	ds_read_b128 v[178:181], v0 offset:2048
	ds_read_b128 v[182:185], v0 offset:3072
	s_add_u32 s24, s24, 0x40000
	s_addc_u32 s25, s25, 0
	s_mov_b32 m0, s36
	v_lshl_add_u64 v[196:197], s[24:25], 0, v[130:131]
	ds_read_b128 v[186:189], v142 offset:32768
	ds_read_b128 v[206:209], v142 offset:33792
	ds_read_b128 v[210:213], v142 offset:34816
	ds_read_b128 v[214:217], v142 offset:35840
	ds_read_b128 v[218:221], v142 offset:36864
	ds_read_b128 v[222:225], v142 offset:37888
	ds_read_b128 v[226:229], v142 offset:38912
	ds_read_b128 v[230:233], v142 offset:39936
	global_load_lds_dwordx4 v[196:197], off
	v_lshl_add_u64 v[196:197], s[24:25], 0, v[132:133]
	s_mov_b32 m0, s37
	s_nop 0
	global_load_lds_dwordx4 v[196:197], off
	s_waitcnt vmcnt(8)
	s_waitcnt lgkmcnt(0)
	s_barrier
	s_setprio 1
	s_waitcnt lgkmcnt(0)
	v_mfma_f32_16x16x32_bf16 v[126:129], v[144:147], v[186:189], v[126:129]
	v_mfma_f32_16x16x32_bf16 v[118:121], v[152:155], v[186:189], v[118:121]
	v_mfma_f32_16x16x32_bf16 v[110:113], v[144:147], v[210:213], v[110:113]
	v_mfma_f32_16x16x32_bf16 v[102:105], v[152:155], v[210:213], v[102:105]
	v_mfma_f32_16x16x32_bf16 v[94:97], v[144:147], v[218:221], v[94:97]
	v_mfma_f32_16x16x32_bf16 v[86:89], v[152:155], v[218:221], v[86:89]
	v_mfma_f32_16x16x32_bf16 v[78:81], v[144:147], v[226:229], v[78:81]
	v_mfma_f32_16x16x32_bf16 v[70:73], v[152:155], v[226:229], v[70:73]
	v_mfma_f32_16x16x32_bf16 v[126:129], v[148:151], v[206:209], v[126:129]
	v_mfma_f32_16x16x32_bf16 v[118:121], v[156:159], v[206:209], v[118:121]
	v_mfma_f32_16x16x32_bf16 v[110:113], v[148:151], v[214:217], v[110:113]
	v_mfma_f32_16x16x32_bf16 v[102:105], v[156:159], v[214:217], v[102:105]
	v_mfma_f32_16x16x32_bf16 v[94:97], v[148:151], v[222:225], v[94:97]
	v_mfma_f32_16x16x32_bf16 v[86:89], v[156:159], v[222:225], v[86:89]
	v_mfma_f32_16x16x32_bf16 v[78:81], v[148:151], v[230:233], v[78:81]
	v_mfma_f32_16x16x32_bf16 v[70:73], v[156:159], v[230:233], v[70:73]
	s_setprio 0
	s_setprio 1
	v_mfma_f32_16x16x32_bf16 v[122:125], v[170:173], v[186:189], v[122:125]
	v_mfma_f32_16x16x32_bf16 v[114:117], v[178:181], v[186:189], v[114:117]
	v_mfma_f32_16x16x32_bf16 v[106:109], v[170:173], v[210:213], v[106:109]
	v_mfma_f32_16x16x32_bf16 v[98:101], v[178:181], v[210:213], v[98:101]
	v_mfma_f32_16x16x32_bf16 v[90:93], v[170:173], v[218:221], v[90:93]
	v_mfma_f32_16x16x32_bf16 v[82:85], v[178:181], v[218:221], v[82:85]
	v_mfma_f32_16x16x32_bf16 v[74:77], v[170:173], v[226:229], v[74:77]
	v_mfma_f32_16x16x32_bf16 v[66:69], v[178:181], v[226:229], v[66:69]
	v_mfma_f32_16x16x32_bf16 v[122:125], v[174:177], v[206:209], v[122:125]
	v_mfma_f32_16x16x32_bf16 v[114:117], v[182:185], v[206:209], v[114:117]
	v_mfma_f32_16x16x32_bf16 v[106:109], v[174:177], v[214:217], v[106:109]
	v_mfma_f32_16x16x32_bf16 v[98:101], v[182:185], v[214:217], v[98:101]
	v_mfma_f32_16x16x32_bf16 v[90:93], v[174:177], v[222:225], v[90:93]
	v_mfma_f32_16x16x32_bf16 v[82:85], v[182:185], v[222:225], v[82:85]
	v_mfma_f32_16x16x32_bf16 v[74:77], v[174:177], v[230:233], v[74:77]
	v_mfma_f32_16x16x32_bf16 v[66:69], v[182:185], v[230:233], v[66:69]
	s_setprio 0
	s_barrier
; #define PG8_STAGE(bufoff, gbase, voff) do { _Pragma("unroll") for (int _i = 0; _i < 2; ++_i) \
;         __builtin_amdgcn_global_load_lds((const unsigned*)((const char*)(gbase) + (voff)[_i]), (LAS unsigned*)(lds + (bufoff) + ldsw + _i * 8192), 16, 0, 0); } while (0)
; #define PG8_LDA(dst, b, h) do { _Pragma("unroll") for (int m = 0; m < 4; ++m) _Pragma("unroll") for (int k = 0; k < 2; ++k) dst[m][k] = *(const LAS bf16x8*)(lds + PG8_SA(b, h) + aoff + m * 2048 + k * 1024); } while (0)
; #define PG8_MMA(ai, bj, At, Bt) do { __builtin_amdgcn_s_setprio(1); _Pragma("unroll") for (int m = 0; m < 4; ++m) _Pragma("unroll") for (int n = 0; n < 2; ++n) _Pragma("unroll") for (int k = 0; k < 2; ++k) \
;         acc[ai][bj][m][n] = __builtin_amdgcn_mfma_f32_16x16x32_bf16(Bt[n][k], At[m][k], acc[ai][bj][m][n], 0, 0, 0); __builtin_amdgcn_s_setprio(0); } while (0)
; #define PG8_WAIT_V(n) asm volatile("s_waitcnt vmcnt(" #n ")" ::: "memory")
; #define PG8_WAIT_L(n) asm volatile("s_waitcnt lgkmcnt(" #n ")" ::: "memory")
; #define PG8_BAR __builtin_amdgcn_s_barrier()
; #define PG8_SCHED __builtin_amdgcn_sched_barrier(0)
; template <class Epi, bool ALIGN_EPI = PG8_ALIGN, bool SP2 = PG8_SP2>
; __device__ __forceinline__ void gemm_phase(LAS unsigned char* lds, const Gemm g, const StaticOrder& S, const Epi& E) {
;     ...
;             PG8_WAIT_V(8); PG8_WAIT_L(0); PG8_BAR; PG8_MMA(0, 0, At, B0); PG8_MMA(0, 1, At, B1); PG8_BAR; PG8_SCHED;
;             PG8_LDA(At, 1, 1); PG8_STAGE(PG8_SB(1, 0), b3, voffB); PG8_STAGE(PG8_SB(1, 1), b3 + hstepB, voffB); PG8_STAGE(PG8_SA(1, 0), a3, voffA);
;             PG8_WAIT_V(8); PG8_WAIT_L(0); PG8_BAR; PG8_MMA(1, 0, At, B0); PG8_MMA(1, 1, At, B1); PG8_BAR; PG8_SCHED;
	s_add_i32 s24, s48, s33
	v_lshl_add_u64 v[160:161], v[160:161], 0, s[50:51]
	s_mov_b32 m0, s24
	ds_read_b128 v[186:189], v142 offset:49152
	ds_read_b128 v[206:209], v142 offset:50176
	ds_read_b128 v[210:213], v142 offset:51200
	ds_read_b128 v[214:217], v142 offset:52224
	ds_read_b128 v[218:221], v142 offset:53248
	ds_read_b128 v[222:225], v142 offset:54272
	ds_read_b128 v[226:229], v142 offset:55296
	ds_read_b128 v[230:233], v142 offset:56320
	global_load_lds_dwordx4 v[160:161], off
	s_add_i32 m0, s24, 0x2000
	s_add_u32 s22, s22, 0x40080
	v_lshl_add_u64 v[160:161], v[164:165], 0, s[50:51]
	s_addc_u32 s23, s23, 0
	s_add_i32 s24, s49, s33
	global_load_lds_dwordx4 v[160:161], off
	v_lshl_add_u64 v[160:161], s[22:23], 0, v[130:131]
	s_mov_b32 m0, s24
	s_nop 0
	global_load_lds_dwordx4 v[160:161], off
	v_lshl_add_u64 v[160:161], s[22:23], 0, v[132:133]
	s_add_i32 m0, s24, 0x2000
	s_nop 0
	global_load_lds_dwordx4 v[160:161], off
	v_lshl_add_u64 v[160:161], v[166:167], 0, s[50:51]
	s_mov_b32 m0, s40
	s_nop 0
	global_load_lds_dwordx4 v[160:161], off
	v_lshl_add_u64 v[160:161], v[194:195], 0, s[50:51]
	s_mov_b32 m0, s41
	s_nop 0
	global_load_lds_dwordx4 v[160:161], off
	s_waitcnt vmcnt(8)
	s_waitcnt lgkmcnt(0)
	s_barrier
	s_setprio 1
	s_waitcnt lgkmcnt(0)
	v_mfma_f32_16x16x32_bf16 v[62:65], v[144:147], v[186:189], v[62:65]
	v_mfma_f32_16x16x32_bf16 v[54:57], v[152:155], v[186:189], v[54:57]
	v_mfma_f32_16x16x32_bf16 v[46:49], v[144:147], v[210:213], v[46:49]
	v_mfma_f32_16x16x32_bf16 v[38:41], v[152:155], v[210:213], v[38:41]
	v_mfma_f32_16x16x32_bf16 v[30:33], v[144:147], v[218:221], v[30:33]
	v_mfma_f32_16x16x32_bf16 v[22:25], v[152:155], v[218:221], v[22:25]
	v_mfma_f32_16x16x32_bf16 v[14:17], v[144:147], v[226:229], v[14:17]
	v_mfma_f32_16x16x32_bf16 v[6:9], v[152:155], v[226:229], v[6:9]
	v_mfma_f32_16x16x32_bf16 v[62:65], v[148:151], v[206:209], v[62:65]
	v_mfma_f32_16x16x32_bf16 v[54:57], v[156:159], v[206:209], v[54:57]
	v_mfma_f32_16x16x32_bf16 v[46:49], v[148:151], v[214:217], v[46:49]
	v_mfma_f32_16x16x32_bf16 v[38:41], v[156:159], v[214:217], v[38:41]
	v_mfma_f32_16x16x32_bf16 v[30:33], v[148:151], v[222:225], v[30:33]
	v_mfma_f32_16x16x32_bf16 v[22:25], v[156:159], v[222:225], v[22:25]
	v_mfma_f32_16x16x32_bf16 v[14:17], v[148:151], v[230:233], v[14:17]
	v_mfma_f32_16x16x32_bf16 v[6:9], v[156:159], v[230:233], v[6:9]
	s_setprio 0
	s_setprio 1
	v_mfma_f32_16x16x32_bf16 v[58:61], v[170:173], v[186:189], v[58:61]
	v_mfma_f32_16x16x32_bf16 v[50:53], v[178:181], v[186:189], v[50:53]
	v_mfma_f32_16x16x32_bf16 v[42:45], v[170:173], v[210:213], v[42:45]
	v_mfma_f32_16x16x32_bf16 v[34:37], v[178:181], v[210:213], v[34:37]
	v_mfma_f32_16x16x32_bf16 v[26:29], v[170:173], v[218:221], v[26:29]
	v_mfma_f32_16x16x32_bf16 v[18:21], v[178:181], v[218:221], v[18:21]
	v_mfma_f32_16x16x32_bf16 v[10:13], v[170:173], v[226:229], v[10:13]
	v_mfma_f32_16x16x32_bf16 v[2:5], v[178:181], v[226:229], v[2:5]
	v_mfma_f32_16x16x32_bf16 v[58:61], v[174:177], v[206:209], v[58:61]
	v_mfma_f32_16x16x32_bf16 v[50:53], v[182:185], v[206:209], v[50:53]
	v_mfma_f32_16x16x32_bf16 v[42:45], v[174:177], v[214:217], v[42:45]
	v_mfma_f32_16x16x32_bf16 v[34:37], v[182:185], v[214:217], v[34:37]
	v_mfma_f32_16x16x32_bf16 v[26:29], v[174:177], v[222:225], v[26:29]
	v_mfma_f32_16x16x32_bf16 v[18:21], v[182:185], v[222:225], v[18:21]
	v_mfma_f32_16x16x32_bf16 v[10:13], v[174:177], v[230:233], v[10:13]
	v_mfma_f32_16x16x32_bf16 v[2:5], v[182:185], v[230:233], v[2:5]
	s_setprio 0
	s_barrier
	s_add_i32 s47, s47, 2
	s_add_u32 s20, s20, 0x100
	s_addc_u32 s21, s21, 0
	s_add_u32 s45, s45, 0x100
	s_addc_u32 s46, s46, 0
	s_cmp_gt_u32 s47, 13
	s_branch .LBB0_611
